# v18 + attention K/V staging loads issued earlier in each half (H1 at segment head, H0 right after the QK MFMA that frees the staging registers); bit-identical
# speedup vs baseline: 1.0040x; 1.0040x over previous
; template <int KB, bool HASY>
; __device__ __forceinline__ void phaseA(f32x16& X0, f32x16& X1, f32x16& Y0, f32x16& Y1, bf16x8& pa0, bf16x8& pa1, bf16x8& pa2, bf16x8& pa3,
;                                        const bf16x8* qr, const f32x16& negm, int kaddr, VFr& vf, int vb, float& l_reg) {
;   SBAR();
;   float ls = 0.f;
;   bf16x8 k0 = rd128<KOFF(KB, 0, 0)>(kaddr), k1 = rd128<KOFF(KB, 1, 0)>(kaddr), k2 = rd128<KOFF(KB, 0, 1)>(kaddr), k3 = rd128<KOFF(KB, 1, 1)>(kaddr);
;   if (HASY) { EXP4(Y0, 0); EXP4(Y0, 4); }
;   SBAR(); WAIT4(k0, k1, k2, k3);
;   bf16x8 k4 = rd128<KOFF(KB, 0, 2)>(kaddr), k5 = rd128<KOFF(KB, 1, 2)>(kaddr), k6 = rd128<KOFF(KB, 0, 3)>(kaddr), k7 = rd128<KOFF(KB, 1, 3)>(kaddr);
;   SBAR();
;   X0 = MF(k0, qr[0], negm); if (HASY) { EXP4(Y0, 8); SUM4(Y0, 0); } SBAR();
;   X1 = MF(k1, qr[0], negm); if (HASY) { EXP4(Y0, 12); SUM4(Y0, 4); } SBAR();
;   X0 = MF(k2, qr[1], X0); if (HASY) { PACK8(Y0, 0, pa0); } SBAR();
;   X1 = MF(k3, qr[1], X1); if (HASY) { EXP4(Y1, 0); SUM4(Y0, 8); } SBAR();
;   WAIT4(k4, k5, k6, k7);
;   bf16x8 k8 = rd128<KOFF(KB, 0, 4)>(kaddr), k9 = rd128<KOFF(KB, 1, 4)>(kaddr), k10 = rd128<KOFF(KB, 0, 5)>(kaddr), k11 = rd128<KOFF(KB, 1, 5)>(kaddr);
;   SBAR();
;   X0 = MF(k4, qr[2], X0); if (HASY) { EXP4(Y1, 4); SUM4(Y0, 12); } SBAR();
;   X1 = MF(k5, qr[2], X1); if (HASY) { PACK8(Y0, 8, pa1); } SBAR();
;   X0 = MF(k6, qr[3], X0); if (HASY) { EXP4(Y1, 8); SUM4(Y1, 0); } SBAR();
;   X1 = MF(k7, qr[3], X1); if (HASY) { EXP4(Y1, 12); SUM4(Y1, 4); } SBAR();
;   WAIT4(k8, k9, k10, k11);
;   SBAR();
;   X0 = MF(k8, qr[4], X0); if (HASY) { PACK8(Y1, 0, pa2); } SBAR();
;   X1 = MF(k9, qr[4], X1); if (HASY) { SUM4(Y1, 8); SUM4(Y1, 12); } SBAR();
;   X0 = MF(k10, qr[5], X0); if (HASY) { PACK8(Y1, 8, pa3); } SBAR();
;   X1 = MF(k11, qr[5], X1); if (HASY) vfr_issue<0>(vf, vb);
;   l_reg += ls;
;   SBAR();
; }
; template <bool HASX>
; __device__ __forceinline__ float phaseB(f32x16* o, bf16x8 pa0, bf16x8 pa1, bf16x8 pa2, bf16x8 pa3, VFr& f, int vb, const f32x16& X0, const f32x16& X1) {
;   SBAR(); VWAIT(f); VFr g; vfr_issue<2>(g, vb); SBAR();
;   float a = 0.f, b = 0.f;
;   o[0] = MF(pa0, PKV(f.a0, f.b0), o[0]); SBAR(); o[1] = MF(pa0, PKV(f.c0, f.d0), o[1]);
;   if (HASX) { a = MX3(X0[0], X0[1], X1[0]); b = MX3(X0[2], X0[3], X1[1]); a = MX3(a, X1[2], X1[3]); b = MX3(b, X0[4], X0[5]); } SBAR();
.LBB0_249:
	s_barrier
	ds_read_b128 v[34:37], v184 offset:0x3400
	ds_read_b128 v[38:41], v184 offset:0x4e00
	ds_read_b128 v[42:45], v184 offset:0x3420
	ds_read_b128 v[46:49], v184 offset:0x4e20
	ds_read_b128 v[170:173], v184 offset:0x3440
	ds_read_b128 v[174:177], v184 offset:0x4e40
	ds_read_b128 v[204:207], v184 offset:0x3460
	ds_read_b128 v[208:211], v184 offset:0x4e60
	s_waitcnt lgkmcnt(7)
	v_mfma_f32_32x32x16_bf16 v[114:129], v[34:37], v[150:153], v[50:65]
	v_exp_f32_e32 v88, v90
	v_exp_f32_e32 v89, v91
	v_exp_f32_e32 v90, v92
	v_exp_f32_e32 v91, v93
	s_waitcnt lgkmcnt(6)
	v_mfma_f32_32x32x16_bf16 v[98:113], v[38:41], v[150:153], v[50:65]
	v_exp_f32_e32 v92, v94
	v_exp_f32_e32 v93, v95
	v_exp_f32_e32 v94, v96
	v_exp_f32_e32 v95, v97
	s_waitcnt lgkmcnt(5)
	v_mfma_f32_32x32x16_bf16 v[114:129], v[42:45], v[146:149], v[114:129]
	v_cvt_pk_bf16_f32 v34, v82, v195
	v_cvt_pk_bf16_f32 v35, v84, v196
	v_cvt_pk_bf16_f32 v36, v83, v85
	v_cvt_pk_bf16_f32 v37, v86, v87
	s_waitcnt lgkmcnt(4)
	v_mfma_f32_32x32x16_bf16 v[98:113], v[46:49], v[146:149], v[98:113]
	v_exp_f32_e32 v96, v66
	v_exp_f32_e32 v97, v67
	v_exp_f32_e32 v197, v68
	v_exp_f32_e32 v198, v69
	ds_read_b128 v[38:41], v184 offset:0x3480
	ds_read_b128 v[66:69], v184 offset:0x4e80
	ds_read_b128 v[212:215], v184 offset:0x34a0
	ds_read_b128 v[216:219], v184 offset:0x4ea0
	s_waitcnt lgkmcnt(4)
	v_mfma_f32_32x32x16_bf16 v[114:129], v[170:173], v[142:145], v[114:129]
	v_exp_f32_e32 v199, v70
	v_exp_f32_e32 v200, v71
	v_exp_f32_e32 v201, v72
	v_exp_f32_e32 v202, v73
	v_mfma_f32_32x32x16_bf16 v[98:113], v[174:177], v[142:145], v[98:113]
	s_add_i32 s18, s52, 0xffffe000
	buffer_load_dwordx4 v[170:173], v185, s[64:67], s18 offen
	buffer_load_dwordx4 v[174:177], v185, s[44:47], s18 offen
	s_add_i32 s28, s68, 0xfffff000
	buffer_load_dwordx4 v[158:161], v186, s[60:63], s28 offen
	v_cvt_pk_bf16_f32 v42, v88, v89
	v_cvt_pk_bf16_f32 v43, v90, v91
	v_cvt_pk_bf16_f32 v44, v92, v93
	v_cvt_pk_bf16_f32 v45, v94, v95
	v_mfma_f32_32x32x16_bf16 v[114:129], v[204:207], v[138:141], v[114:129]
	v_exp_f32_e32 v203, v74
	v_exp_f32_e32 v204, v75
	v_exp_f32_e32 v205, v76
	v_exp_f32_e32 v206, v77
	v_mfma_f32_32x32x16_bf16 v[98:113], v[208:211], v[138:141], v[98:113]
	v_exp_f32_e32 v207, v78
	v_exp_f32_e32 v208, v79
	v_exp_f32_e32 v209, v80
	v_exp_f32_e32 v210, v81
	s_waitcnt lgkmcnt(0)
	s_nop 0
	v_mfma_f32_32x32x16_bf16 v[114:129], v[38:41], v[134:137], v[114:129]
	v_cvt_pk_bf16_f32 v46, v96, v97
	v_cvt_pk_bf16_f32 v47, v197, v198
	v_cvt_pk_bf16_f32 v48, v199, v200
	v_cvt_pk_bf16_f32 v49, v201, v202
	v_mfma_f32_32x32x16_bf16 v[98:113], v[66:69], v[134:137], v[98:113]
	v_mfma_f32_32x32x16_bf16 v[114:129], v[212:215], v[130:133], v[114:129]
	v_cvt_pk_bf16_f32 v38, v203, v204
	v_cvt_pk_bf16_f32 v39, v205, v206
	v_cvt_pk_bf16_f32 v40, v207, v208
	v_cvt_pk_bf16_f32 v41, v209, v210
	ds_read_b64_tr_b16 v[78:79], v0 offset:0
	ds_read_b64_tr_b16 v[80:81], v0 offset:0x400
	ds_read_b64_tr_b16 v[74:75], v0 offset:0x200
	v_mfma_f32_32x32x16_bf16 v[98:113], v[216:219], v[130:133], v[98:113]
	ds_read_b64_tr_b16 v[76:77], v0 offset:0x600
	ds_read_b64_tr_b16 v[70:71], v0 offset:0x800
	ds_read_b64_tr_b16 v[72:73], v0 offset:0xc00
	ds_read_b64_tr_b16 v[66:67], v0 offset:0xa00
	ds_read_b64_tr_b16 v[68:69], v0 offset:0xe00
	s_waitcnt lgkmcnt(0)
	ds_read_b64_tr_b16 v[212:213], v0 offset:0x1000
	ds_read_b64_tr_b16 v[214:215], v0 offset:0x1400
	ds_read_b64_tr_b16 v[216:217], v0 offset:0x1200
	ds_read_b64_tr_b16 v[218:219], v0 offset:0x1600
	ds_read_b64_tr_b16 v[220:221], v0 offset:0x1800
	ds_read_b64_tr_b16 v[222:223], v0 offset:0x1c00
	ds_read_b64_tr_b16 v[228:229], v0 offset:0x1a00
	ds_read_b64_tr_b16 v[230:231], v0 offset:0x1e00
	v_mfma_f32_32x32x16_bf16 v[18:33], v[34:37], v[78:81], v[18:33]
	v_add_f32_e32 v238, v82, v195
	v_add_f32_e32 v239, v84, v196
	v_add_f32_e32 v240, v83, v85
	v_add_f32_e32 v241, v86, v87
	v_add_f32_e32 v238, v238, v239
	v_add_f32_e32 v240, v240, v241
	v_mfma_f32_32x32x16_bf16 v[2:17], v[34:37], v[74:77], v[2:17]
	v_max_f32_e32 v34, v114, v115
	v_max3_f32 v35, v116, v117, v99
	v_max3_f32 v34, v34, v98, v100
	v_max3_f32 v35, v35, v118, v119
	v_mfma_f32_32x32x16_bf16 v[18:33], v[42:45], v[70:73], v[18:33]
	v_max3_f32 v34, v34, v101, v120
	v_max3_f32 v35, v35, v102, v103
	v_add_f32_e32 v238, v240, v238
	v_add_f32_e32 v239, v88, v89
	v_add_f32_e32 v241, v90, v91
	v_mfma_f32_32x32x16_bf16 v[2:17], v[42:45], v[66:69], v[2:17]
	v_max3_f32 v34, v34, v121, v104
	v_max3_f32 v34, v34, v105, v124
	v_max3_f32 v35, v35, v122, v123
	v_add_f32_e32 v239, v239, v241
	v_add_f32_e32 v240, v92, v93
	v_add_f32_e32 v241, v94, v95
	s_waitcnt lgkmcnt(0)
	v_mfma_f32_32x32x16_bf16 v[18:33], v[46:49], v[212:215], v[18:33]
	v_max3_f32 v34, v34, v125, v108
	v_max3_f32 v35, v35, v106, v107
	v_add_f32_e32 v238, v239, v238
	v_add_f32_e32 v240, v240, v241
	s_waitcnt vmcnt(3)
	v_add_u32_e32 v67, s69, v187
	ds_write_b128 v67, v[162:165]
	v_mfma_f32_32x32x16_bf16 v[2:17], v[46:49], v[216:219], v[2:17]
	v_max3_f32 v34, v34, v109, v128
	v_max3_f32 v35, v35, v126, v127
	v_add_f32_e32 v238, v240, v238
	v_add_f32_e32 v239, v96, v97
	v_add_f32_e32 v241, v197, v198
	s_waitcnt vmcnt(2)
	ds_write_b128 v188, v[166:169] offset:24576
	v_mfma_f32_32x32x16_bf16 v[18:33], v[38:41], v[220:223], v[18:33]
	v_max3_f32 v34, v34, v129, v112
	v_max3_f32 v35, v35, v110, v111
	v_add_f32_e32 v239, v239, v241
	v_add_f32_e32 v240, v199, v200
	v_add_f32_e32 v241, v201, v202
	ds_write_b128 v193, v[154:157] offset:24704
	v_add_f32_e32 v238, v239, v238
	v_add_f32_e32 v240, v240, v241
	v_mfma_f32_32x32x16_bf16 v[2:17], v[38:41], v[228:231], v[2:17]
	v_max3_f32 v34, v34, v113, v35
	v_cmp_lt_f32_e32 vcc, s35, v34
	v_add_f32_e32 v238, v240, v238
	v_add_f32_e32 v239, v203, v204
	v_add_f32_e32 v241, v205, v206
	v_add_f32_e32 v239, v239, v241
	v_add_f32_e32 v240, v207, v208
	v_add_f32_e32 v241, v209, v210
	v_add_f32_e32 v238, v239, v238
	v_add_f32_e32 v240, v240, v241
	v_add_f32_e32 v238, v240, v238
	v_add_f32_e32 v194, v194, v238
	s_cbranch_vccnz .LBB0_272
; template <int KB, bool HASY>
; __device__ __forceinline__ void phaseA(f32x16& X0, f32x16& X1, f32x16& Y0, f32x16& Y1, bf16x8& pa0, bf16x8& pa1, bf16x8& pa2, bf16x8& pa3,
;                                        const bf16x8* qr, const f32x16& negm, int kaddr, VFr& vf, int vb, float& l_reg) {
;   SBAR();
;   float ls = 0.f;
;   bf16x8 k0 = rd128<KOFF(KB, 0, 0)>(kaddr), k1 = rd128<KOFF(KB, 1, 0)>(kaddr), k2 = rd128<KOFF(KB, 0, 1)>(kaddr), k3 = rd128<KOFF(KB, 1, 1)>(kaddr);
;   if (HASY) { EXP4(Y0, 0); EXP4(Y0, 4); }
;   SBAR(); WAIT4(k0, k1, k2, k3);
;   bf16x8 k4 = rd128<KOFF(KB, 0, 2)>(kaddr), k5 = rd128<KOFF(KB, 1, 2)>(kaddr), k6 = rd128<KOFF(KB, 0, 3)>(kaddr), k7 = rd128<KOFF(KB, 1, 3)>(kaddr);
;   SBAR();
;   X0 = MF(k0, qr[0], negm); if (HASY) { EXP4(Y0, 8); SUM4(Y0, 0); } SBAR();
;   X1 = MF(k1, qr[0], negm); if (HASY) { EXP4(Y0, 12); SUM4(Y0, 4); } SBAR();
;   X0 = MF(k2, qr[1], X0); if (HASY) { PACK8(Y0, 0, pa0); } SBAR();
;   X1 = MF(k3, qr[1], X1); if (HASY) { EXP4(Y1, 0); SUM4(Y0, 8); } SBAR();
;   WAIT4(k4, k5, k6, k7);
;   bf16x8 k8 = rd128<KOFF(KB, 0, 4)>(kaddr), k9 = rd128<KOFF(KB, 1, 4)>(kaddr), k10 = rd128<KOFF(KB, 0, 5)>(kaddr), k11 = rd128<KOFF(KB, 1, 5)>(kaddr);
;   SBAR();
;   X0 = MF(k4, qr[2], X0); if (HASY) { EXP4(Y1, 4); SUM4(Y0, 12); } SBAR();
;   X1 = MF(k5, qr[2], X1); if (HASY) { PACK8(Y0, 8, pa1); } SBAR();
;   X0 = MF(k6, qr[3], X0); if (HASY) { EXP4(Y1, 8); SUM4(Y1, 0); } SBAR();
;   X1 = MF(k7, qr[3], X1); if (HASY) { EXP4(Y1, 12); SUM4(Y1, 4); } SBAR();
;   WAIT4(k8, k9, k10, k11);
;   SBAR();
;   X0 = MF(k8, qr[4], X0); if (HASY) { PACK8(Y1, 0, pa2); } SBAR();
;   X1 = MF(k9, qr[4], X1); if (HASY) { SUM4(Y1, 8); SUM4(Y1, 12); } SBAR();
;   X0 = MF(k10, qr[5], X0); if (HASY) { PACK8(Y1, 8, pa3); } SBAR();
;   X1 = MF(k11, qr[5], X1); if (HASY) vfr_issue<0>(vf, vb);
;   l_reg += ls;
;   SBAR();
; }
; template <bool HASX>
; __device__ __forceinline__ float phaseB(f32x16* o, bf16x8 pa0, bf16x8 pa1, bf16x8 pa2, bf16x8 pa3, VFr& f, int vb, const f32x16& X0, const f32x16& X1) {
;   SBAR(); VWAIT(f); VFr g; vfr_issue<2>(g, vb); SBAR();
;   float a = 0.f, b = 0.f;
;   o[0] = MF(pa0, PKV(f.a0, f.b0), o[0]); SBAR(); o[1] = MF(pa0, PKV(f.c0, f.d0), o[1]);
;   if (HASX) { a = MX3(X0[0], X0[1], X1[0]); b = MX3(X0[2], X0[3], X1[1]); a = MX3(a, X1[2], X1[3]); b = MX3(b, X0[4], X0[5]); } SBAR();
.LBB0_259:
	v_add_u32_e32 v237, s76, v192
	v_exp_f32_e32 v195, v114
	v_exp_f32_e32 v197, v115
	v_exp_f32_e32 v198, v116
	v_exp_f32_e32 v201, v117
	v_exp_f32_e32 v196, v118
	v_exp_f32_e32 v199, v119
	v_exp_f32_e32 v200, v120
	v_exp_f32_e32 v202, v121
	s_waitcnt lgkmcnt(0)
	s_barrier
	ds_read_b128 v[66:69], v184 offset:0
	ds_read_b128 v[212:215], v184 offset:0x1a00
	ds_read_b128 v[216:219], v184 offset:32
	ds_read_b128 v[118:121], v184 offset:0x1a20
	ds_read_b128 v[220:223], v184 offset:64
	ds_read_b128 v[228:231], v184 offset:0x1a40
	ds_read_b128 v[238:241], v184 offset:0x60
	ds_read_b128 v[242:245], v184 offset:0x1a60
	s_cmp_ge_u32 s39, s38
	s_cselect_b64 s[18:19], -1, 0
	s_and_b64 vcc, exec, s[18:19]
	s_cbranch_vccnz .LBB0_263
	buffer_load_dwordx4 v[162:165], v185, s[64:67], s52 offen
	buffer_load_dwordx4 v[166:169], v185, s[44:47], s52 offen
	buffer_load_dwordx4 v[154:157], v186, s[60:63], s68 offen
.LBB0_263:
	s_waitcnt lgkmcnt(7)
	v_mfma_f32_32x32x16_bf16 v[82:97], v[66:69], v[150:153], v[50:65]
	v_exp_f32_e32 v203, v122
	v_exp_f32_e32 v204, v123
	v_exp_f32_e32 v205, v124
	v_exp_f32_e32 v206, v125
	s_waitcnt lgkmcnt(6)
	v_mfma_f32_32x32x16_bf16 v[66:81], v[212:215], v[150:153], v[50:65]
	v_exp_f32_e32 v207, v126
	v_exp_f32_e32 v208, v127
	v_exp_f32_e32 v209, v128
	v_exp_f32_e32 v210, v129
	s_waitcnt lgkmcnt(5)
	v_mfma_f32_32x32x16_bf16 v[82:97], v[216:219], v[146:149], v[82:97]
	v_cvt_pk_bf16_f32 v114, v195, v197
	v_cvt_pk_bf16_f32 v115, v198, v201
	v_cvt_pk_bf16_f32 v116, v196, v199
	v_cvt_pk_bf16_f32 v117, v200, v202
	s_waitcnt lgkmcnt(4)
	v_mfma_f32_32x32x16_bf16 v[66:81], v[118:121], v[146:149], v[66:81]
	v_exp_f32_e32 v211, v98
	v_exp_f32_e32 v212, v99
	v_exp_f32_e32 v213, v100
	v_exp_f32_e32 v214, v101
	ds_read_b128 v[98:101], v184 offset:0x80
	ds_read_b128 v[118:121], v184 offset:0x1a80
	ds_read_b128 v[122:125], v184 offset:0xa0
	ds_read_b128 v[246:249], v184 offset:0x1aa0
	s_waitcnt lgkmcnt(4)
	v_mfma_f32_32x32x16_bf16 v[82:97], v[220:223], v[142:145], v[82:97]
	v_exp_f32_e32 v215, v102
	v_exp_f32_e32 v216, v103
	v_exp_f32_e32 v217, v104
	v_exp_f32_e32 v218, v105
	v_mfma_f32_32x32x16_bf16 v[66:81], v[228:231], v[142:145], v[66:81]
	v_cvt_pk_bf16_f32 v102, v203, v204
	v_cvt_pk_bf16_f32 v103, v205, v206
	v_cvt_pk_bf16_f32 v104, v207, v208
	v_cvt_pk_bf16_f32 v105, v209, v210
	v_mfma_f32_32x32x16_bf16 v[82:97], v[238:241], v[138:141], v[82:97]
	v_exp_f32_e32 v219, v106
	v_exp_f32_e32 v220, v107
	v_exp_f32_e32 v221, v108
	v_exp_f32_e32 v222, v109
	v_mfma_f32_32x32x16_bf16 v[66:81], v[242:245], v[138:141], v[66:81]
	v_exp_f32_e32 v223, v110
	v_exp_f32_e32 v234, v111
	v_exp_f32_e32 v235, v112
	v_exp_f32_e32 v236, v113
	s_waitcnt lgkmcnt(0)
	s_nop 0
	v_mfma_f32_32x32x16_bf16 v[82:97], v[98:101], v[134:137], v[82:97]
	v_cvt_pk_bf16_f32 v106, v211, v212
	v_cvt_pk_bf16_f32 v107, v213, v214
	v_cvt_pk_bf16_f32 v108, v215, v216
	v_cvt_pk_bf16_f32 v109, v217, v218
	v_mfma_f32_32x32x16_bf16 v[66:81], v[118:121], v[134:137], v[66:81]
	v_mfma_f32_32x32x16_bf16 v[82:97], v[122:125], v[130:133], v[82:97]
	v_cvt_pk_bf16_f32 v98, v219, v220
	v_cvt_pk_bf16_f32 v99, v221, v222
	v_cvt_pk_bf16_f32 v100, v223, v234
	v_cvt_pk_bf16_f32 v101, v235, v236
	ds_read_b64_tr_b16 v[126:127], v237 offset:0
	ds_read_b64_tr_b16 v[128:129], v237 offset:0x400
	ds_read_b64_tr_b16 v[122:123], v237 offset:0x200
	v_mfma_f32_32x32x16_bf16 v[66:81], v[246:249], v[130:133], v[66:81]
	ds_read_b64_tr_b16 v[124:125], v237 offset:0x600
	ds_read_b64_tr_b16 v[118:119], v237 offset:0x800
	ds_read_b64_tr_b16 v[120:121], v237 offset:0xc00
	ds_read_b64_tr_b16 v[110:111], v237 offset:0xa00
	ds_read_b64_tr_b16 v[112:113], v237 offset:0xe00
	s_waitcnt lgkmcnt(0)
	ds_read_b64_tr_b16 v[228:229], v237 offset:0x1000
	ds_read_b64_tr_b16 v[230:231], v237 offset:0x1400
	ds_read_b64_tr_b16 v[238:239], v237 offset:0x1200
	ds_read_b64_tr_b16 v[240:241], v237 offset:0x1600
	ds_read_b64_tr_b16 v[242:243], v237 offset:0x1800
	ds_read_b64_tr_b16 v[244:245], v237 offset:0x1c00
	ds_read_b64_tr_b16 v[246:247], v237 offset:0x1a00
	ds_read_b64_tr_b16 v[248:249], v237 offset:0x1e00
	v_mfma_f32_32x32x16_bf16 v[18:33], v[114:117], v[126:129], v[18:33]
	v_add_f32_e32 v34, v195, v197
	v_add_f32_e32 v35, v198, v201
	v_add_f32_e32 v36, v196, v199
	v_add_f32_e32 v37, v200, v202
	v_add_f32_e32 v34, v34, v35
	v_add_f32_e32 v36, v36, v37
	v_mfma_f32_32x32x16_bf16 v[2:17], v[114:117], v[122:125], v[2:17]
	v_max_f32_e32 v114, v82, v83
	v_max3_f32 v115, v84, v85, v67
	v_max3_f32 v114, v114, v66, v68
	v_max3_f32 v115, v115, v86, v87
	v_mfma_f32_32x32x16_bf16 v[18:33], v[102:105], v[118:121], v[18:33]
	v_max3_f32 v114, v114, v69, v88
	v_max3_f32 v115, v115, v70, v71
	v_add_f32_e32 v34, v36, v34
	v_add_f32_e32 v35, v203, v204
	v_add_f32_e32 v37, v205, v206
	v_mfma_f32_32x32x16_bf16 v[2:17], v[102:105], v[110:113], v[2:17]
	v_max3_f32 v102, v114, v89, v72
	v_max3_f32 v103, v115, v90, v91
	v_max3_f32 v102, v102, v73, v92
	v_add_f32_e32 v35, v35, v37
	v_add_f32_e32 v36, v207, v208
	v_add_f32_e32 v37, v209, v210
	s_waitcnt lgkmcnt(0)
	v_mfma_f32_32x32x16_bf16 v[18:33], v[106:109], v[228:231], v[18:33]
	v_max3_f32 v103, v103, v74, v75
	v_max3_f32 v102, v102, v93, v76
	v_add_f32_e32 v34, v35, v34
	v_add_f32_e32 v36, v36, v37
	s_cmp_ge_u32 s39, s38
	s_cbranch_scc0 .Lmy_h1w
	s_waitcnt vmcnt(0)

; template <int KB, bool HASY>
; __device__ __forceinline__ void phaseA(f32x16& X0, f32x16& X1, f32x16& Y0, f32x16& Y1, bf16x8& pa0, bf16x8& pa1, bf16x8& pa2, bf16x8& pa3,
;                                        const bf16x8* qr, const f32x16& negm, int kaddr, VFr& vf, int vb, float& l_reg) {
;   SBAR();
;   float ls = 0.f;
;   bf16x8 k0 = rd128<KOFF(KB, 0, 0)>(kaddr), k1 = rd128<KOFF(KB, 1, 0)>(kaddr), k2 = rd128<KOFF(KB, 0, 1)>(kaddr), k3 = rd128<KOFF(KB, 1, 1)>(kaddr);
;   if (HASY) { EXP4(Y0, 0); EXP4(Y0, 4); }
;   SBAR(); WAIT4(k0, k1, k2, k3);
;   bf16x8 k4 = rd128<KOFF(KB, 0, 2)>(kaddr), k5 = rd128<KOFF(KB, 1, 2)>(kaddr), k6 = rd128<KOFF(KB, 0, 3)>(kaddr), k7 = rd128<KOFF(KB, 1, 3)>(kaddr);
;   SBAR();
;   X0 = MF(k0, qr[0], negm); if (HASY) { EXP4(Y0, 8); SUM4(Y0, 0); } SBAR();
;   X1 = MF(k1, qr[0], negm); if (HASY) { EXP4(Y0, 12); SUM4(Y0, 4); } SBAR();
;   X0 = MF(k2, qr[1], X0); if (HASY) { PACK8(Y0, 0, pa0); } SBAR();
;   X1 = MF(k3, qr[1], X1); if (HASY) { EXP4(Y1, 0); SUM4(Y0, 8); } SBAR();
;   WAIT4(k4, k5, k6, k7);
;   bf16x8 k8 = rd128<KOFF(KB, 0, 4)>(kaddr), k9 = rd128<KOFF(KB, 1, 4)>(kaddr), k10 = rd128<KOFF(KB, 0, 5)>(kaddr), k11 = rd128<KOFF(KB, 1, 5)>(kaddr);
;   SBAR();
;   X0 = MF(k4, qr[2], X0); if (HASY) { EXP4(Y1, 4); SUM4(Y0, 12); } SBAR();
;   X1 = MF(k5, qr[2], X1); if (HASY) { PACK8(Y0, 8, pa1); } SBAR();
;   X0 = MF(k6, qr[3], X0); if (HASY) { EXP4(Y1, 8); SUM4(Y1, 0); } SBAR();
;   X1 = MF(k7, qr[3], X1); if (HASY) { EXP4(Y1, 12); SUM4(Y1, 4); } SBAR();
;   WAIT4(k8, k9, k10, k11);
;   SBAR();
;   X0 = MF(k8, qr[4], X0); if (HASY) { PACK8(Y1, 0, pa2); } SBAR();
;   X1 = MF(k9, qr[4], X1); if (HASY) { SUM4(Y1, 8); SUM4(Y1, 12); } SBAR();
;   X0 = MF(k10, qr[5], X0); if (HASY) { PACK8(Y1, 8, pa3); } SBAR();
;   X1 = MF(k11, qr[5], X1); if (HASY) vfr_issue<0>(vf, vb);
;   l_reg += ls;
;   SBAR();
; }
; template <bool HASX>
; __device__ __forceinline__ float phaseB(f32x16* o, bf16x8 pa0, bf16x8 pa1, bf16x8 pa2, bf16x8 pa3, VFr& f, int vb, const f32x16& X0, const f32x16& X1) {
;   SBAR(); VWAIT(f); VFr g; vfr_issue<2>(g, vb); SBAR();
;   float a = 0.f, b = 0.f;
;   o[0] = MF(pa0, PKV(f.a0, f.b0), o[0]); SBAR(); o[1] = MF(pa0, PKV(f.c0, f.d0), o[1]);
;   if (HASX) { a = MX3(X0[0], X0[1], X1[0]); b = MX3(X0[2], X0[3], X1[1]); a = MX3(a, X1[2], X1[3]); b = MX3(b, X0[4], X0[5]); } SBAR();
.Lmy_y249:
	s_barrier
	ds_read_b128 v[34:37], v184 offset:0x3400
	ds_read_b128 v[38:41], v184 offset:0x4e00
	ds_read_b128 v[42:45], v184 offset:0x3420
	ds_read_b128 v[46:49], v184 offset:0x4e20
	ds_read_b128 v[170:173], v184 offset:0x3440
	ds_read_b128 v[174:177], v184 offset:0x4e40
	ds_read_b128 v[204:207], v184 offset:0x3460
	ds_read_b128 v[208:211], v184 offset:0x4e60
	s_waitcnt lgkmcnt(7)
	v_mfma_f32_32x32x16_bf16 v[114:129], v[34:37], v[150:153], v[50:65]
	v_exp_f32_e32 v88, v90
	v_exp_f32_e32 v89, v91
	v_exp_f32_e32 v90, v92
	v_exp_f32_e32 v91, v93
	s_waitcnt lgkmcnt(6)
	v_mfma_f32_32x32x16_bf16 v[98:113], v[38:41], v[150:153], v[50:65]
	v_exp_f32_e32 v92, v94
	v_exp_f32_e32 v93, v95
	v_exp_f32_e32 v94, v96
	v_exp_f32_e32 v95, v97
	s_waitcnt lgkmcnt(5)
	v_mfma_f32_32x32x16_bf16 v[114:129], v[42:45], v[146:149], v[114:129]
	v_cvt_pk_bf16_f32 v34, v82, v195
	v_cvt_pk_bf16_f32 v35, v84, v196
	v_cvt_pk_bf16_f32 v36, v83, v85
	v_cvt_pk_bf16_f32 v37, v86, v87
	s_waitcnt lgkmcnt(4)
	v_mfma_f32_32x32x16_bf16 v[98:113], v[46:49], v[146:149], v[98:113]
	v_exp_f32_e32 v96, v66
	v_exp_f32_e32 v97, v67
	v_exp_f32_e32 v197, v68
	v_exp_f32_e32 v198, v69
	ds_read_b128 v[38:41], v184 offset:0x3480
	ds_read_b128 v[66:69], v184 offset:0x4e80
	ds_read_b128 v[212:215], v184 offset:0x34a0
	ds_read_b128 v[216:219], v184 offset:0x4ea0
	s_waitcnt lgkmcnt(4)
	v_mfma_f32_32x32x16_bf16 v[114:129], v[170:173], v[142:145], v[114:129]
	v_exp_f32_e32 v199, v70
	v_exp_f32_e32 v200, v71
	v_exp_f32_e32 v201, v72
	v_exp_f32_e32 v202, v73
	v_mfma_f32_32x32x16_bf16 v[98:113], v[174:177], v[142:145], v[98:113]
	s_add_i32 s18, s52, 0xffffe000
	buffer_load_dwordx4 v[170:173], v185, s[64:67], s18 offen
	buffer_load_dwordx4 v[174:177], v185, s[44:47], s18 offen
	v_cvt_pk_bf16_f32 v42, v88, v89
	v_cvt_pk_bf16_f32 v43, v90, v91
	v_cvt_pk_bf16_f32 v44, v92, v93
	v_cvt_pk_bf16_f32 v45, v94, v95
	v_mfma_f32_32x32x16_bf16 v[114:129], v[204:207], v[138:141], v[114:129]
	v_exp_f32_e32 v203, v74
	v_exp_f32_e32 v204, v75
	v_exp_f32_e32 v205, v76
	v_exp_f32_e32 v206, v77
	v_mfma_f32_32x32x16_bf16 v[98:113], v[208:211], v[138:141], v[98:113]
	v_exp_f32_e32 v207, v78
	v_exp_f32_e32 v208, v79
	v_exp_f32_e32 v209, v80
	v_exp_f32_e32 v210, v81
	s_waitcnt lgkmcnt(0)
	s_nop 0
	v_mfma_f32_32x32x16_bf16 v[114:129], v[38:41], v[134:137], v[114:129]
	v_cvt_pk_bf16_f32 v46, v96, v97
	v_cvt_pk_bf16_f32 v47, v197, v198
	v_cvt_pk_bf16_f32 v48, v199, v200
	v_cvt_pk_bf16_f32 v49, v201, v202
	v_mfma_f32_32x32x16_bf16 v[98:113], v[66:69], v[134:137], v[98:113]
	v_mfma_f32_32x32x16_bf16 v[114:129], v[212:215], v[130:133], v[114:129]
	v_cvt_pk_bf16_f32 v38, v203, v204
	v_cvt_pk_bf16_f32 v39, v205, v206
	v_cvt_pk_bf16_f32 v40, v207, v208
	v_cvt_pk_bf16_f32 v41, v209, v210
	ds_read_b64_tr_b16 v[78:79], v0 offset:0
	ds_read_b64_tr_b16 v[80:81], v0 offset:0x400
	ds_read_b64_tr_b16 v[74:75], v0 offset:0x200
	v_mfma_f32_32x32x16_bf16 v[98:113], v[216:219], v[130:133], v[98:113]
	ds_read_b64_tr_b16 v[76:77], v0 offset:0x600
	ds_read_b64_tr_b16 v[70:71], v0 offset:0x800
	ds_read_b64_tr_b16 v[72:73], v0 offset:0xc00
	ds_read_b64_tr_b16 v[66:67], v0 offset:0xa00
	ds_read_b64_tr_b16 v[68:69], v0 offset:0xe00
	s_waitcnt lgkmcnt(0)
	ds_read_b64_tr_b16 v[212:213], v0 offset:0x1000
	ds_read_b64_tr_b16 v[214:215], v0 offset:0x1400
	ds_read_b64_tr_b16 v[216:217], v0 offset:0x1200
	ds_read_b64_tr_b16 v[218:219], v0 offset:0x1600
	ds_read_b64_tr_b16 v[220:221], v0 offset:0x1800
	ds_read_b64_tr_b16 v[222:223], v0 offset:0x1c00
	ds_read_b64_tr_b16 v[228:229], v0 offset:0x1a00
	ds_read_b64_tr_b16 v[230:231], v0 offset:0x1e00
	v_mfma_f32_32x32x16_bf16 v[18:33], v[34:37], v[78:81], v[18:33]
	v_add_f32_e32 v238, v82, v195
	v_add_f32_e32 v239, v84, v196
	v_add_f32_e32 v240, v83, v85
	v_add_f32_e32 v241, v86, v87
	v_add_f32_e32 v238, v238, v239
	v_add_f32_e32 v240, v240, v241
	v_mfma_f32_32x32x16_bf16 v[2:17], v[34:37], v[74:77], v[2:17]
	v_max_f32_e32 v34, v114, v115
	v_max3_f32 v35, v116, v117, v99
	v_max3_f32 v34, v34, v98, v100
	v_max3_f32 v35, v35, v118, v119
	v_mfma_f32_32x32x16_bf16 v[18:33], v[42:45], v[70:73], v[18:33]
	v_max3_f32 v34, v34, v101, v120
	v_max3_f32 v35, v35, v102, v103
	v_add_f32_e32 v238, v240, v238
	v_add_f32_e32 v239, v88, v89
	v_add_f32_e32 v241, v90, v91
	v_mfma_f32_32x32x16_bf16 v[2:17], v[42:45], v[66:69], v[2:17]
	v_max3_f32 v34, v34, v121, v104
	v_max3_f32 v34, v34, v105, v124
	v_max3_f32 v35, v35, v122, v123
	v_add_f32_e32 v239, v239, v241
	v_add_f32_e32 v240, v92, v93
	v_add_f32_e32 v241, v94, v95
	s_waitcnt lgkmcnt(0)
	v_mfma_f32_32x32x16_bf16 v[18:33], v[46:49], v[212:215], v[18:33]
	v_max3_f32 v34, v34, v125, v108
	v_max3_f32 v35, v35, v106, v107
	v_add_f32_e32 v238, v239, v238
	v_add_f32_e32 v240, v240, v241
	s_waitcnt vmcnt(3)
	v_add_u32_e32 v67, s69, v187
	ds_write_b128 v67, v[162:165]
	v_mfma_f32_32x32x16_bf16 v[2:17], v[46:49], v[216:219], v[2:17]
	v_max3_f32 v34, v34, v109, v128
	v_max3_f32 v35, v35, v126, v127
	v_add_f32_e32 v238, v240, v238
	v_add_f32_e32 v239, v96, v97
	v_add_f32_e32 v241, v197, v198
	s_waitcnt vmcnt(2)
	ds_write_b128 v188, v[166:169] offset:24576
	v_mfma_f32_32x32x16_bf16 v[18:33], v[38:41], v[220:223], v[18:33]
	v_max3_f32 v34, v34, v129, v112
	v_max3_f32 v35, v35, v110, v111
	v_add_f32_e32 v239, v239, v241
	v_add_f32_e32 v240, v199, v200
	v_add_f32_e32 v241, v201, v202
	v_add_f32_e32 v238, v239, v238
	v_add_f32_e32 v240, v240, v241
	v_mfma_f32_32x32x16_bf16 v[2:17], v[38:41], v[228:231], v[2:17]
	v_max3_f32 v34, v34, v113, v35
	v_cmp_lt_f32_e32 vcc, s35, v34
	v_add_f32_e32 v238, v240, v238
	v_add_f32_e32 v239, v203, v204
	v_add_f32_e32 v241, v205, v206
	v_add_f32_e32 v239, v239, v241
	v_add_f32_e32 v240, v207, v208
	v_add_f32_e32 v241, v209, v210
	v_add_f32_e32 v238, v239, v238
	v_add_f32_e32 v240, v240, v241
	v_add_f32_e32 v238, v240, v238
	v_add_f32_e32 v194, v194, v238
	s_cbranch_vccnz .Lmy_y272
.Lmy_y259:
	v_add_u32_e32 v237, s76, v192
	v_exp_f32_e32 v195, v114
	v_exp_f32_e32 v197, v115
	v_exp_f32_e32 v198, v116
	v_exp_f32_e32 v201, v117
	v_exp_f32_e32 v196, v118
	v_exp_f32_e32 v199, v119
	v_exp_f32_e32 v200, v120
	v_exp_f32_e32 v202, v121
	s_waitcnt lgkmcnt(0)
	s_barrier
	ds_read_b128 v[66:69], v184 offset:0
	ds_read_b128 v[212:215], v184 offset:0x1a00
	ds_read_b128 v[216:219], v184 offset:32
	ds_read_b128 v[118:121], v184 offset:0x1a20
	ds_read_b128 v[220:223], v184 offset:64
	ds_read_b128 v[228:231], v184 offset:0x1a40
	ds_read_b128 v[238:241], v184 offset:0x60
	ds_read_b128 v[242:245], v184 offset:0x1a60
	s_cmp_ge_u32 s39, s38
	s_cselect_b64 s[18:19], -1, 0
	s_and_b64 vcc, exec, s[18:19]
	s_cbranch_vccnz .Lmy_y263
	buffer_load_dwordx4 v[162:165], v185, s[64:67], s52 offen
	buffer_load_dwordx4 v[166:169], v185, s[44:47], s52 offen
